# residual-stream f32 loads/stores in the down / w_out epilogues marked nt (streamed once)
# baseline (speedup 1.0000x reference)
; __device__ __forceinline__ unsigned cvtpk(float lo, float hi) { f32x2 v = {lo, hi}; bf16x2_t b = __builtin_convertvector(v, bf16x2_t); return __builtin_bit_cast(unsigned, b); }
; #define SWZ_XOR(v, m) __uint_as_float((unsigned)__builtin_amdgcn_ds_swizzle((int)__float_as_uint(v), ((m) << 10) | 0x1f))
; __device__ __forceinline__ float sum32x(float v) { auto rr = __builtin_amdgcn_permlane32_swap(__float_as_uint(v), __float_as_uint(v), false, false); return __uint_as_float(rr[0]) + __uint_as_float(rr[1]); }
;     __device__ __forceinline__ void operator()(const pg8::f32x4 (&acc)[2][2][4][2], const pg8::Unit& u, int wr, int wc, int fr, int fq) const {
;     ...
;         } else if (kind == EK_RES) {
; #pragma unroll
;             for (int ai = 0; ai < 2; ++ai) {
;                 pg8::f32x4 pre[4][2][2];
; #pragma unroll
;                 for (int m = 0; m < 4; ++m) {
;                     const size_t ro = (size_t)(rowb + 128 * ai + 16 * m) * ldc + colb;
; #pragma unroll
;                     for (int bj = 0; bj < 2; ++bj)
; #pragma unroll
;                         for (int n = 0; n < 2; ++n) pre[m][bj][n] = *(const pg8::f32x4*)(fin + ro + 128 * bj + NS * n);
;                 }
; #pragma unroll
;                 for (int m = 0; m < 4; ++m) {
;                     const size_t ro = (size_t)(rowb + 128 * ai + 16 * m) * ldc + colb;
;                     float ssr = 0.f;
; #pragma unroll
;                     for (int bj = 0; bj < 2; ++bj)
; #pragma unroll
;                         for (int n = 0; n < 2; ++n) {
;                             const size_t off = ro + 128 * bj + NS * n;
;                             const pg8::f32x4 v = pre[m][bj][n] + acc[ai][bj][m][n] * coef;
;                             *(pg8::f32x4*)(fout + off) = v;
;                             if (flags & 2) { u32x2 w; w.x = cvtpk(v[0], v[1]); w.y = cvtpk(v[2], v[3]); *(u32x2*)(o0 + off) = w; ssr += (v[0] * v[0] + v[1] * v[1]) + (v[2] * v[2] + v[3] * v[3]); }
;                         }
;                     if (flags & 2) { ssr += SWZ_XOR(ssr, 16); ssr = sum32x(ssr); if (fq == 0) atomicAdd((float*)o1 + (rowb + 128 * ai + 16 * m), ssr); }
;                 }
.LBB0_1068:
	s_andn2_b64 vcc, exec, s[8:9]
	s_cbranch_vccnz .LBB0_1118
	v_ashrrev_i32_e32 v231, 31, v230
	v_or_b32_e32 v64, 16, v228
	v_lshl_add_u64 v[234:235], v[230:231], 2, v[136:137]
	v_mad_i64_i32 v[140:141], s[8:9], v65, v228, 0
	v_mad_i64_i32 v[240:241], s[8:9], v65, v64, 0
	v_or_b32_e32 v64, 32, v228
	v_lshl_add_u64 v[140:141], v[140:141], 2, v[234:235]
	v_mad_i64_i32 v[238:239], s[8:9], v65, v64, 0
	v_or_b32_e32 v64, 48, v228
	global_load_dword v66, v215, s[40:41] offset:1040
	global_load_dwordx4 v[204:207], v[140:141], off nt
	global_load_dwordx4 v[196:199], v[140:141], off offset:16 nt
	global_load_dwordx4 v[188:191], v[140:141], off offset:528 nt
	global_load_dwordx4 v[192:195], v[140:141], off offset:512 nt
	v_lshl_add_u64 v[140:141], v[240:241], 2, v[234:235]
	v_mad_i64_i32 v[236:237], s[8:9], v65, v64, 0
	global_load_dwordx4 v[180:183], v[140:141], off offset:16 nt
	global_load_dwordx4 v[184:187], v[140:141], off nt
	global_load_dwordx4 v[172:175], v[140:141], off offset:528 nt
	global_load_dwordx4 v[176:179], v[140:141], off offset:512 nt
	v_lshl_add_u64 v[140:141], v[238:239], 2, v[234:235]
	v_lshl_add_u64 v[144:145], v[236:237], 2, v[234:235]
	global_load_dwordx4 v[164:167], v[140:141], off offset:16 nt
	global_load_dwordx4 v[168:171], v[140:141], off nt
	global_load_dwordx4 v[156:159], v[140:141], off offset:528 nt
	global_load_dwordx4 v[160:163], v[140:141], off offset:512 nt
	global_load_dwordx4 v[148:151], v[144:145], off offset:16 nt
	global_load_dwordx4 v[152:155], v[144:145], off nt
	s_nop 0
	global_load_dwordx4 v[140:143], v[144:145], off offset:528 nt
	s_nop 0
	global_load_dwordx4 v[144:147], v[144:145], off offset:512 nt
	v_and_b32_e32 v64, 2, v67
	v_cmp_ne_u32_e64 s[10:11], 0, v64
	v_mad_i64_i32 v[202:203], s[18:19], v65, v228, v[230:231]
	v_ashrrev_i32_e32 v229, 31, v228
	s_mov_b64 s[8:9], -1
	v_lshl_add_u64 v[242:243], v[202:203], 2, v[138:139]
	s_and_b64 vcc, exec, s[10:11]
	s_waitcnt vmcnt(16)
	v_mov_b32_e32 v232, v66
	v_mov_b32_e32 v233, v66
	s_waitcnt vmcnt(15)
	v_pk_fma_f32 v[212:213], v[134:135], v[66:67], v[206:207] op_sel_hi:[1,0,1]
	v_pk_fma_f32 v[210:211], v[132:133], v[66:67], v[204:205] op_sel_hi:[1,0,1]
	s_waitcnt vmcnt(14)
	v_pk_fma_f32 v[208:209], v[128:129], v[232:233], v[196:197]
	s_waitcnt vmcnt(12)
	v_pk_fma_f32 v[204:205], v[124:125], v[232:233], v[192:193]
	v_pk_fma_f32 v[200:201], v[120:121], v[232:233], v[188:189]
	global_store_dwordx4 v[242:243], v[210:213], off nt
	s_cbranch_vccz .LBB0_1073
	v_mul_f32_e32 v64, v211, v211
	v_mul_f32_e32 v67, v213, v213
	v_fmac_f32_e32 v64, v210, v210
	v_fmac_f32_e32 v67, v212, v212
	v_add_f32_e32 v64, v64, v67
	v_mov_b32_e32 v67, v66
	v_cvt_pk_bf16_f32 v188, v210, v211
	v_cvt_pk_bf16_f32 v189, v212, v213
	v_lshl_add_u64 v[192:193], v[202:203], 1, v[68:69]
	v_pk_fma_f32 v[210:211], v[130:131], v[66:67], v[198:199]
	global_store_dwordx2 v[192:193], v[188:189], off
	v_cvt_pk_bf16_f32 v188, v208, v209
	v_cvt_pk_bf16_f32 v189, v210, v211
	global_store_dwordx4 v[242:243], v[208:211], off offset:16 nt
	global_store_dwordx2 v[192:193], v[188:189], off offset:8
	v_mul_f32_e32 v188, v209, v209
	v_mul_f32_e32 v189, v211, v211
	v_fmac_f32_e32 v188, v208, v208
	v_fmac_f32_e32 v189, v210, v210
	v_add_f32_e32 v188, v188, v189
	v_pk_fma_f32 v[206:207], v[126:127], v[66:67], v[194:195]
	v_add_f32_e32 v64, v64, v188
	v_cvt_pk_bf16_f32 v188, v204, v205
	v_cvt_pk_bf16_f32 v189, v206, v207
	global_store_dwordx4 v[242:243], v[204:207], off offset:512 nt
	global_store_dwordx2 v[192:193], v[188:189], off offset:256
	v_mul_f32_e32 v188, v205, v205
	v_mul_f32_e32 v189, v207, v207
	v_fmac_f32_e32 v188, v204, v204
	v_fmac_f32_e32 v189, v206, v206
	v_add_f32_e32 v188, v188, v189
	v_pk_fma_f32 v[202:203], v[122:123], v[66:67], v[190:191]
	v_add_f32_e32 v64, v188, v64
	v_mul_f32_e32 v67, v201, v201
	v_mul_f32_e32 v188, v203, v203
	v_fmac_f32_e32 v67, v200, v200
	v_fmac_f32_e32 v188, v202, v202
	v_add_f32_e32 v67, v67, v188
	v_add_f32_e32 v64, v67, v64
	ds_swizzle_b32 v67, v64 offset:swizzle(SWAP,16)
	v_cvt_pk_bf16_f32 v188, v200, v201
	v_cvt_pk_bf16_f32 v189, v202, v203
	global_store_dwordx4 v[242:243], v[200:203], off offset:528 nt
	global_store_dwordx2 v[192:193], v[188:189], off offset:264
	s_waitcnt lgkmcnt(0)
	v_add_f32_e32 v64, v64, v67
	v_mov_b32_e32 v67, v64
	s_nop 1
	v_permlane32_swap_b32_e32 v64, v67
	s_and_saveexec_b64 s[8:9], s[4:5]
	s_cbranch_execz .LBB0_1072
	v_lshl_add_u64 v[188:189], v[228:229], 2, v[70:71]
	v_add_f32_e32 v64, v64, v67
	global_atomic_add_f32 v[188:189], v64, off

; __device__ __forceinline__ unsigned cvtpk(float lo, float hi) { f32x2 v = {lo, hi}; bf16x2_t b = __builtin_convertvector(v, bf16x2_t); return __builtin_bit_cast(unsigned, b); }
; #define SWZ_XOR(v, m) __uint_as_float((unsigned)__builtin_amdgcn_ds_swizzle((int)__float_as_uint(v), ((m) << 10) | 0x1f))
; __device__ __forceinline__ float sum32x(float v) { auto rr = __builtin_amdgcn_permlane32_swap(__float_as_uint(v), __float_as_uint(v), false, false); return __uint_as_float(rr[0]) + __uint_as_float(rr[1]); }
;     __device__ __forceinline__ void operator()(const pg8::f32x4 (&acc)[2][2][4][2], const pg8::Unit& u, int wr, int wc, int fr, int fq) const {
;     ...
;                 for (int m = 0; m < 4; ++m) {
;                     const size_t ro = (size_t)(rowb + 128 * ai + 16 * m) * ldc + colb;
;                     float ssr = 0.f;
; #pragma unroll
;                     for (int bj = 0; bj < 2; ++bj)
; #pragma unroll
;                         for (int n = 0; n < 2; ++n) {
;                             const size_t off = ro + 128 * bj + NS * n;
;                             const pg8::f32x4 v = pre[m][bj][n] + acc[ai][bj][m][n] * coef;
;                             *(pg8::f32x4*)(fout + off) = v;
;                             if (flags & 2) { u32x2 w; w.x = cvtpk(v[0], v[1]); w.y = cvtpk(v[2], v[3]); *(u32x2*)(o0 + off) = w; ssr += (v[0] * v[0] + v[1] * v[1]) + (v[2] * v[2] + v[3] * v[3]); }
;                         }
;                     if (flags & 2) { ssr += SWZ_XOR(ssr, 16); ssr = sum32x(ssr); if (fq == 0) atomicAdd((float*)o1 + (rowb + 128 * ai + 16 * m), ssr); }
;                 }
.LBB0_1073:
	s_andn2_b64 vcc, exec, s[8:9]
	s_cbranch_vccnz .LBB0_1075
	v_mov_b32_e32 v67, v66
	v_pk_fma_f32 v[210:211], v[130:131], v[66:67], v[198:199]
	v_pk_fma_f32 v[206:207], v[126:127], v[66:67], v[194:195]
	v_pk_fma_f32 v[202:203], v[122:123], v[66:67], v[190:191]
	global_store_dwordx4 v[242:243], v[208:211], off offset:16 nt
	global_store_dwordx4 v[242:243], v[204:207], off offset:512 nt
	global_store_dwordx4 v[242:243], v[200:203], off offset:528 nt
.LBB0_1075:
	v_lshl_add_u64 v[190:191], v[240:241], 0, v[230:231]
	v_mov_b32_e32 v67, v66
	v_cndmask_b32_e64 v64, 0, 1, s[10:11]
	s_waitcnt vmcnt(11)
	v_pk_fma_f32 v[196:197], v[118:119], v[66:67], v[186:187]
	v_pk_fma_f32 v[194:195], v[116:117], v[232:233], v[184:185]
	v_lshl_add_u64 v[198:199], v[190:191], 2, v[138:139]
	s_mov_b64 s[48:49], -1
	v_cmp_ne_u32_e64 s[8:9], 1, v64
	s_andn2_b64 vcc, exec, s[10:11]
	v_pk_fma_f32 v[192:193], v[108:109], v[232:233], v[180:181]
	s_waitcnt vmcnt(9)
	v_pk_fma_f32 v[188:189], v[112:113], v[232:233], v[176:177]
	v_pk_fma_f32 v[184:185], v[104:105], v[232:233], v[172:173]
	global_store_dwordx4 v[198:199], v[194:197], off nt
	s_cbranch_vccnz .LBB0_1079
	v_cvt_pk_bf16_f32 v172, v194, v195
	v_cvt_pk_bf16_f32 v173, v196, v197
	v_lshl_add_u64 v[176:177], v[190:191], 1, v[68:69]
	global_store_dwordx2 v[176:177], v[172:173], off
	v_mul_f32_e32 v64, v195, v195
	v_mul_f32_e32 v172, v197, v197
	v_fmac_f32_e32 v64, v194, v194
	v_fmac_f32_e32 v172, v196, v196
	v_pk_fma_f32 v[194:195], v[110:111], v[66:67], v[182:183]
	v_add_f32_e32 v64, v64, v172
	v_cvt_pk_bf16_f32 v172, v192, v193
	v_cvt_pk_bf16_f32 v173, v194, v195
	global_store_dwordx4 v[198:199], v[192:195], off offset:16 nt
	global_store_dwordx2 v[176:177], v[172:173], off offset:8
	v_mul_f32_e32 v172, v193, v193
	v_mul_f32_e32 v173, v195, v195
	v_fmac_f32_e32 v172, v192, v192
	v_fmac_f32_e32 v173, v194, v194
	v_add_f32_e32 v172, v172, v173
	v_pk_fma_f32 v[190:191], v[114:115], v[66:67], v[178:179]
	v_add_f32_e32 v64, v64, v172
	v_cvt_pk_bf16_f32 v172, v188, v189
	v_cvt_pk_bf16_f32 v173, v190, v191
	global_store_dwordx4 v[198:199], v[188:191], off offset:512 nt
	global_store_dwordx2 v[176:177], v[172:173], off offset:256
	v_mul_f32_e32 v172, v189, v189
	v_mul_f32_e32 v173, v191, v191
	v_fmac_f32_e32 v172, v188, v188
	v_fmac_f32_e32 v173, v190, v190
	v_add_f32_e32 v172, v172, v173
	v_pk_fma_f32 v[186:187], v[106:107], v[66:67], v[174:175]
	v_add_f32_e32 v64, v64, v172
	v_mul_f32_e32 v67, v185, v185
	v_mul_f32_e32 v172, v187, v187
	v_fmac_f32_e32 v67, v184, v184
	v_fmac_f32_e32 v172, v186, v186
	v_add_f32_e32 v67, v67, v172
	v_add_f32_e32 v64, v64, v67
	ds_swizzle_b32 v67, v64 offset:swizzle(SWAP,16)
	v_cvt_pk_bf16_f32 v172, v184, v185
	v_cvt_pk_bf16_f32 v173, v186, v187
	global_store_dwordx4 v[198:199], v[184:187], off offset:528 nt
	global_store_dwordx2 v[176:177], v[172:173], off offset:264
	s_waitcnt lgkmcnt(0)
	v_add_f32_e32 v64, v64, v67
	v_mov_b32_e32 v67, v64
	s_nop 1
	v_permlane32_swap_b32_e32 v64, v67
	s_and_saveexec_b64 s[10:11], s[4:5]
	s_cbranch_execz .LBB0_1078
	v_lshl_add_u64 v[172:173], v[228:229], 2, v[70:71]
	v_add_f32_e32 v64, v64, v67
	global_atomic_add_f32 v[172:173], v64, off offset:64

; __device__ __forceinline__ unsigned cvtpk(float lo, float hi) { f32x2 v = {lo, hi}; bf16x2_t b = __builtin_convertvector(v, bf16x2_t); return __builtin_bit_cast(unsigned, b); }
; #define SWZ_XOR(v, m) __uint_as_float((unsigned)__builtin_amdgcn_ds_swizzle((int)__float_as_uint(v), ((m) << 10) | 0x1f))
; __device__ __forceinline__ float sum32x(float v) { auto rr = __builtin_amdgcn_permlane32_swap(__float_as_uint(v), __float_as_uint(v), false, false); return __uint_as_float(rr[0]) + __uint_as_float(rr[1]); }
;     __device__ __forceinline__ void operator()(const pg8::f32x4 (&acc)[2][2][4][2], const pg8::Unit& u, int wr, int wc, int fr, int fq) const {
;     ...
;                 for (int m = 0; m < 4; ++m) {
;                     const size_t ro = (size_t)(rowb + 128 * ai + 16 * m) * ldc + colb;
;                     float ssr = 0.f;
; #pragma unroll
;                     for (int bj = 0; bj < 2; ++bj)
; #pragma unroll
;                         for (int n = 0; n < 2; ++n) {
;                             const size_t off = ro + 128 * bj + NS * n;
;                             const pg8::f32x4 v = pre[m][bj][n] + acc[ai][bj][m][n] * coef;
;                             *(pg8::f32x4*)(fout + off) = v;
;                             if (flags & 2) { u32x2 w; w.x = cvtpk(v[0], v[1]); w.y = cvtpk(v[2], v[3]); *(u32x2*)(o0 + off) = w; ssr += (v[0] * v[0] + v[1] * v[1]) + (v[2] * v[2] + v[3] * v[3]); }
;                         }
;                     if (flags & 2) { ssr += SWZ_XOR(ssr, 16); ssr = sum32x(ssr); if (fq == 0) atomicAdd((float*)o1 + (rowb + 128 * ai + 16 * m), ssr); }
;                 }
.LBB0_1079:
	s_andn2_b64 vcc, exec, s[48:49]
	s_cbranch_vccnz .LBB0_1081
	v_mov_b32_e32 v67, v66
	v_pk_fma_f32 v[194:195], v[110:111], v[66:67], v[182:183]
	v_pk_fma_f32 v[190:191], v[114:115], v[66:67], v[178:179]
	v_pk_fma_f32 v[186:187], v[106:107], v[66:67], v[174:175]
	global_store_dwordx4 v[198:199], v[192:195], off offset:16 nt
	global_store_dwordx4 v[198:199], v[188:191], off offset:512 nt
	global_store_dwordx4 v[198:199], v[184:187], off offset:528 nt
.LBB0_1081:
	v_lshl_add_u64 v[174:175], v[238:239], 0, v[230:231]
	v_mov_b32_e32 v67, v66
	s_waitcnt vmcnt(8)
	v_pk_fma_f32 v[180:181], v[102:103], v[66:67], v[170:171]
	v_pk_fma_f32 v[178:179], v[100:101], v[232:233], v[168:169]
	v_lshl_add_u64 v[182:183], v[174:175], 2, v[138:139]
	s_mov_b64 s[10:11], -1
	s_and_b64 vcc, exec, s[8:9]
	v_pk_fma_f32 v[176:177], v[92:93], v[232:233], v[164:165]
	s_waitcnt vmcnt(6)
	v_pk_fma_f32 v[172:173], v[96:97], v[232:233], v[160:161]
	v_pk_fma_f32 v[168:169], v[88:89], v[232:233], v[156:157]
	global_store_dwordx4 v[182:183], v[178:181], off nt
	s_cbranch_vccnz .LBB0_1085
	v_cvt_pk_bf16_f32 v156, v178, v179
	v_cvt_pk_bf16_f32 v157, v180, v181
	v_lshl_add_u64 v[160:161], v[174:175], 1, v[68:69]
	global_store_dwordx2 v[160:161], v[156:157], off
	v_mul_f32_e32 v64, v179, v179
	v_mul_f32_e32 v156, v181, v181
	v_fmac_f32_e32 v64, v178, v178
	v_fmac_f32_e32 v156, v180, v180
	v_pk_fma_f32 v[178:179], v[94:95], v[66:67], v[166:167]
	v_add_f32_e32 v64, v64, v156
	v_cvt_pk_bf16_f32 v156, v176, v177
	v_cvt_pk_bf16_f32 v157, v178, v179
	global_store_dwordx4 v[182:183], v[176:179], off offset:16 nt
	global_store_dwordx2 v[160:161], v[156:157], off offset:8
	v_mul_f32_e32 v156, v177, v177
	v_mul_f32_e32 v157, v179, v179
	v_fmac_f32_e32 v156, v176, v176
	v_fmac_f32_e32 v157, v178, v178
	v_add_f32_e32 v156, v156, v157
	v_pk_fma_f32 v[174:175], v[98:99], v[66:67], v[162:163]
	v_add_f32_e32 v64, v64, v156
	v_cvt_pk_bf16_f32 v156, v172, v173
	v_cvt_pk_bf16_f32 v157, v174, v175
	global_store_dwordx4 v[182:183], v[172:175], off offset:512 nt
	global_store_dwordx2 v[160:161], v[156:157], off offset:256
	v_mul_f32_e32 v156, v173, v173
	v_mul_f32_e32 v157, v175, v175
	v_fmac_f32_e32 v156, v172, v172
	v_fmac_f32_e32 v157, v174, v174
	v_add_f32_e32 v156, v156, v157
	v_pk_fma_f32 v[170:171], v[90:91], v[66:67], v[158:159]
	v_add_f32_e32 v64, v64, v156
	v_mul_f32_e32 v67, v169, v169
	v_mul_f32_e32 v156, v171, v171
	v_fmac_f32_e32 v67, v168, v168
	v_fmac_f32_e32 v156, v170, v170
	v_add_f32_e32 v67, v67, v156
	v_add_f32_e32 v64, v64, v67
	ds_swizzle_b32 v67, v64 offset:swizzle(SWAP,16)
	v_cvt_pk_bf16_f32 v156, v168, v169
	v_cvt_pk_bf16_f32 v157, v170, v171
	global_store_dwordx4 v[182:183], v[168:171], off offset:528 nt
	global_store_dwordx2 v[160:161], v[156:157], off offset:264
	s_waitcnt lgkmcnt(0)
	v_add_f32_e32 v64, v64, v67
	v_mov_b32_e32 v67, v64
	s_nop 1
	v_permlane32_swap_b32_e32 v64, v67
	s_and_saveexec_b64 s[10:11], s[4:5]
	s_cbranch_execz .LBB0_1084
	v_lshl_add_u64 v[156:157], v[228:229], 2, v[70:71]
	v_add_f32_e32 v64, v64, v67
	global_atomic_add_f32 v[156:157], v64, off offset:128

; __device__ __forceinline__ unsigned cvtpk(float lo, float hi) { f32x2 v = {lo, hi}; bf16x2_t b = __builtin_convertvector(v, bf16x2_t); return __builtin_bit_cast(unsigned, b); }
; #define SWZ_XOR(v, m) __uint_as_float((unsigned)__builtin_amdgcn_ds_swizzle((int)__float_as_uint(v), ((m) << 10) | 0x1f))
; __device__ __forceinline__ float sum32x(float v) { auto rr = __builtin_amdgcn_permlane32_swap(__float_as_uint(v), __float_as_uint(v), false, false); return __uint_as_float(rr[0]) + __uint_as_float(rr[1]); }
;     __device__ __forceinline__ void operator()(const pg8::f32x4 (&acc)[2][2][4][2], const pg8::Unit& u, int wr, int wc, int fr, int fq) const {
;     ...
;                 for (int m = 0; m < 4; ++m) {
;                     const size_t ro = (size_t)(rowb + 128 * ai + 16 * m) * ldc + colb;
;                     float ssr = 0.f;
; #pragma unroll
;                     for (int bj = 0; bj < 2; ++bj)
; #pragma unroll
;                         for (int n = 0; n < 2; ++n) {
;                             const size_t off = ro + 128 * bj + NS * n;
;                             const pg8::f32x4 v = pre[m][bj][n] + acc[ai][bj][m][n] * coef;
;                             *(pg8::f32x4*)(fout + off) = v;
;                             if (flags & 2) { u32x2 w; w.x = cvtpk(v[0], v[1]); w.y = cvtpk(v[2], v[3]); *(u32x2*)(o0 + off) = w; ssr += (v[0] * v[0] + v[1] * v[1]) + (v[2] * v[2] + v[3] * v[3]); }
;                         }
;                     if (flags & 2) { ssr += SWZ_XOR(ssr, 16); ssr = sum32x(ssr); if (fq == 0) atomicAdd((float*)o1 + (rowb + 128 * ai + 16 * m), ssr); }
;                 }
.LBB0_1085:
	s_andn2_b64 vcc, exec, s[10:11]
	s_cbranch_vccnz .LBB0_1087
	v_mov_b32_e32 v67, v66
	v_pk_fma_f32 v[178:179], v[94:95], v[66:67], v[166:167]
	v_pk_fma_f32 v[174:175], v[98:99], v[66:67], v[162:163]
	v_pk_fma_f32 v[170:171], v[90:91], v[66:67], v[158:159]
	global_store_dwordx4 v[182:183], v[176:179], off offset:16 nt
	global_store_dwordx4 v[182:183], v[172:175], off offset:512 nt
	global_store_dwordx4 v[182:183], v[168:171], off offset:528 nt
.LBB0_1087:
	v_lshl_add_u64 v[158:159], v[236:237], 0, v[230:231]
	v_mov_b32_e32 v67, v66
	s_waitcnt vmcnt(5)
	v_pk_fma_f32 v[164:165], v[86:87], v[66:67], v[154:155]
	v_pk_fma_f32 v[162:163], v[84:85], v[232:233], v[152:153]
	v_lshl_add_u64 v[166:167], v[158:159], 2, v[138:139]
	s_mov_b64 s[10:11], -1
	s_and_b64 vcc, exec, s[8:9]
	v_pk_fma_f32 v[160:161], v[76:77], v[232:233], v[148:149]
	s_waitcnt vmcnt(3)
	v_pk_fma_f32 v[156:157], v[80:81], v[232:233], v[144:145]
	v_pk_fma_f32 v[152:153], v[72:73], v[232:233], v[140:141]
	global_store_dwordx4 v[166:167], v[162:165], off nt
	s_cbranch_vccnz .LBB0_1091
	v_cvt_pk_bf16_f32 v140, v162, v163
	v_cvt_pk_bf16_f32 v141, v164, v165
	v_lshl_add_u64 v[144:145], v[158:159], 1, v[68:69]
	global_store_dwordx2 v[144:145], v[140:141], off
	v_mul_f32_e32 v64, v163, v163
	v_mul_f32_e32 v140, v165, v165
	v_fmac_f32_e32 v64, v162, v162
	v_fmac_f32_e32 v140, v164, v164
	v_pk_fma_f32 v[162:163], v[78:79], v[66:67], v[150:151]
	v_add_f32_e32 v64, v64, v140
	v_cvt_pk_bf16_f32 v140, v160, v161
	v_cvt_pk_bf16_f32 v141, v162, v163
	global_store_dwordx4 v[166:167], v[160:163], off offset:16 nt
	global_store_dwordx2 v[144:145], v[140:141], off offset:8
	v_mul_f32_e32 v140, v161, v161
	v_mul_f32_e32 v141, v163, v163
	v_fmac_f32_e32 v140, v160, v160
	v_fmac_f32_e32 v141, v162, v162
	v_add_f32_e32 v140, v140, v141
	v_pk_fma_f32 v[158:159], v[82:83], v[66:67], v[146:147]
	v_add_f32_e32 v64, v64, v140
	v_cvt_pk_bf16_f32 v140, v156, v157
	v_cvt_pk_bf16_f32 v141, v158, v159
	global_store_dwordx4 v[166:167], v[156:159], off offset:512 nt
	global_store_dwordx2 v[144:145], v[140:141], off offset:256
	v_mul_f32_e32 v140, v157, v157
	v_mul_f32_e32 v141, v159, v159
	v_fmac_f32_e32 v140, v156, v156
	v_fmac_f32_e32 v141, v158, v158
	v_add_f32_e32 v140, v140, v141
	v_pk_fma_f32 v[154:155], v[74:75], v[66:67], v[142:143]
	v_add_f32_e32 v64, v64, v140
	v_mul_f32_e32 v67, v153, v153
	v_mul_f32_e32 v140, v155, v155
	v_fmac_f32_e32 v67, v152, v152
	v_fmac_f32_e32 v140, v154, v154
	v_add_f32_e32 v67, v67, v140
	v_add_f32_e32 v64, v64, v67
	ds_swizzle_b32 v67, v64 offset:swizzle(SWAP,16)
	v_cvt_pk_bf16_f32 v140, v152, v153
	v_cvt_pk_bf16_f32 v141, v154, v155
	global_store_dwordx4 v[166:167], v[152:155], off offset:528 nt
	global_store_dwordx2 v[144:145], v[140:141], off offset:264
	s_waitcnt lgkmcnt(0)
	v_add_f32_e32 v64, v64, v67
	v_mov_b32_e32 v67, v64
	s_nop 1
	v_permlane32_swap_b32_e32 v64, v67
	s_and_saveexec_b64 s[10:11], s[4:5]
	s_cbranch_execz .LBB0_1090
	v_lshl_add_u64 v[140:141], v[228:229], 2, v[70:71]
	v_add_f32_e32 v64, v64, v67
	global_atomic_add_f32 v[140:141], v64, off offset:192

; __device__ __forceinline__ unsigned cvtpk(float lo, float hi) { f32x2 v = {lo, hi}; bf16x2_t b = __builtin_convertvector(v, bf16x2_t); return __builtin_bit_cast(unsigned, b); }
; #define SWZ_XOR(v, m) __uint_as_float((unsigned)__builtin_amdgcn_ds_swizzle((int)__float_as_uint(v), ((m) << 10) | 0x1f))
; __device__ __forceinline__ float sum32x(float v) { auto rr = __builtin_amdgcn_permlane32_swap(__float_as_uint(v), __float_as_uint(v), false, false); return __uint_as_float(rr[0]) + __uint_as_float(rr[1]); }
;     __device__ __forceinline__ void operator()(const pg8::f32x4 (&acc)[2][2][4][2], const pg8::Unit& u, int wr, int wc, int fr, int fq) const {
;     ...
;         } else if (kind == EK_RES) {
; #pragma unroll
;             for (int ai = 0; ai < 2; ++ai) {
;                 pg8::f32x4 pre[4][2][2];
; #pragma unroll
;                 for (int m = 0; m < 4; ++m) {
;                     const size_t ro = (size_t)(rowb + 128 * ai + 16 * m) * ldc + colb;
; #pragma unroll
;                     for (int bj = 0; bj < 2; ++bj)
; #pragma unroll
;                         for (int n = 0; n < 2; ++n) pre[m][bj][n] = *(const pg8::f32x4*)(fin + ro + 128 * bj + NS * n);
;                 }
; #pragma unroll
;                 for (int m = 0; m < 4; ++m) {
;                     const size_t ro = (size_t)(rowb + 128 * ai + 16 * m) * ldc + colb;
;                     float ssr = 0.f;
; #pragma unroll
;                     for (int bj = 0; bj < 2; ++bj)
; #pragma unroll
;                         for (int n = 0; n < 2; ++n) {
;                             const size_t off = ro + 128 * bj + NS * n;
;                             const pg8::f32x4 v = pre[m][bj][n] + acc[ai][bj][m][n] * coef;
;                             *(pg8::f32x4*)(fout + off) = v;
;                             if (flags & 2) { u32x2 w; w.x = cvtpk(v[0], v[1]); w.y = cvtpk(v[2], v[3]); *(u32x2*)(o0 + off) = w; ssr += (v[0] * v[0] + v[1] * v[1]) + (v[2] * v[2] + v[3] * v[3]); }
;                         }
;                     if (flags & 2) { ssr += SWZ_XOR(ssr, 16); ssr = sum32x(ssr); if (fq == 0) atomicAdd((float*)o1 + (rowb + 128 * ai + 16 * m), ssr); }
;                 }
.LBB0_1091:
	s_andn2_b64 vcc, exec, s[10:11]
	s_cbranch_vccnz .LBB0_1093
	v_mov_b32_e32 v67, v66
	v_pk_fma_f32 v[162:163], v[78:79], v[66:67], v[150:151]
	v_pk_fma_f32 v[158:159], v[82:83], v[66:67], v[146:147]
	v_pk_fma_f32 v[154:155], v[74:75], v[66:67], v[142:143]
	global_store_dwordx4 v[166:167], v[160:163], off offset:16 nt
	global_store_dwordx4 v[166:167], v[156:159], off offset:512 nt
	global_store_dwordx4 v[166:167], v[152:155], off offset:528 nt
.LBB0_1093:
	v_add_u32_e32 v64, 0x80, v228
	v_add_u32_e32 v67, 0x90, v228
	v_mad_i64_i32 v[140:141], s[10:11], v65, v64, 0
	v_mad_i64_i32 v[240:241], s[10:11], v65, v67, 0
	v_add_u32_e32 v67, 0xa0, v228
	v_lshl_add_u64 v[140:141], v[140:141], 2, v[234:235]
	v_mad_i64_i32 v[238:239], s[10:11], v65, v67, 0
	v_add_u32_e32 v67, 0xb0, v228
	global_load_dwordx4 v[204:207], v[140:141], off nt
	global_load_dwordx4 v[196:199], v[140:141], off offset:16 nt
	global_load_dwordx4 v[188:191], v[140:141], off offset:528 nt
	global_load_dwordx4 v[192:195], v[140:141], off offset:512 nt
	v_lshl_add_u64 v[140:141], v[240:241], 2, v[234:235]
	v_mad_i64_i32 v[236:237], s[10:11], v65, v67, 0
	global_load_dwordx4 v[180:183], v[140:141], off offset:16 nt
	global_load_dwordx4 v[184:187], v[140:141], off nt
	global_load_dwordx4 v[172:175], v[140:141], off offset:528 nt
	global_load_dwordx4 v[176:179], v[140:141], off offset:512 nt
	v_lshl_add_u64 v[140:141], v[238:239], 2, v[234:235]
	v_lshl_add_u64 v[144:145], v[236:237], 2, v[234:235]
	global_load_dwordx4 v[164:167], v[140:141], off offset:16 nt
	global_load_dwordx4 v[168:171], v[140:141], off nt
	global_load_dwordx4 v[156:159], v[140:141], off offset:528 nt
	global_load_dwordx4 v[160:163], v[140:141], off offset:512 nt
	global_load_dwordx4 v[148:151], v[144:145], off offset:16 nt
	global_load_dwordx4 v[152:155], v[144:145], off nt
	s_nop 0
	global_load_dwordx4 v[140:143], v[144:145], off offset:528 nt
	s_nop 0
	global_load_dwordx4 v[144:147], v[144:145], off offset:512 nt
	v_mad_i64_i32 v[202:203], s[10:11], v65, v64, v[230:231]
	v_mov_b32_e32 v67, v66
	v_lshl_add_u64 v[234:235], v[202:203], 2, v[138:139]
	s_mov_b64 s[10:11], -1
	s_and_b64 vcc, exec, s[8:9]
	s_waitcnt vmcnt(15)
	v_pk_fma_f32 v[212:213], v[62:63], v[66:67], v[206:207]
	v_pk_fma_f32 v[210:211], v[60:61], v[232:233], v[204:205]
	s_waitcnt vmcnt(14)
	v_pk_fma_f32 v[208:209], v[52:53], v[232:233], v[196:197]
	s_waitcnt vmcnt(12)
	v_pk_fma_f32 v[204:205], v[56:57], v[232:233], v[192:193]
	v_pk_fma_f32 v[200:201], v[48:49], v[232:233], v[188:189]
	global_store_dwordx4 v[234:235], v[210:213], off nt
	s_cbranch_vccnz .LBB0_1097
	v_cvt_pk_bf16_f32 v188, v210, v211
	v_cvt_pk_bf16_f32 v189, v212, v213
	v_lshl_add_u64 v[192:193], v[202:203], 1, v[68:69]
	global_store_dwordx2 v[192:193], v[188:189], off
	v_mul_f32_e32 v64, v211, v211
	v_mul_f32_e32 v188, v213, v213
	v_fmac_f32_e32 v64, v210, v210
	v_fmac_f32_e32 v188, v212, v212
	v_pk_fma_f32 v[210:211], v[54:55], v[66:67], v[198:199]
	v_add_f32_e32 v64, v64, v188
	v_cvt_pk_bf16_f32 v188, v208, v209
	v_cvt_pk_bf16_f32 v189, v210, v211
	global_store_dwordx4 v[234:235], v[208:211], off offset:16 nt
	global_store_dwordx2 v[192:193], v[188:189], off offset:8
	v_mul_f32_e32 v188, v209, v209
	v_mul_f32_e32 v189, v211, v211
	v_fmac_f32_e32 v188, v208, v208
	v_fmac_f32_e32 v189, v210, v210
	v_add_f32_e32 v188, v188, v189
	v_pk_fma_f32 v[206:207], v[58:59], v[66:67], v[194:195]
	v_add_f32_e32 v64, v64, v188
	v_cvt_pk_bf16_f32 v188, v204, v205
	v_cvt_pk_bf16_f32 v189, v206, v207
	global_store_dwordx4 v[234:235], v[204:207], off offset:512 nt
	global_store_dwordx2 v[192:193], v[188:189], off offset:256
	v_mul_f32_e32 v188, v205, v205
	v_mul_f32_e32 v189, v207, v207
	v_fmac_f32_e32 v188, v204, v204
	v_fmac_f32_e32 v189, v206, v206
	v_add_f32_e32 v188, v188, v189
	v_pk_fma_f32 v[202:203], v[50:51], v[66:67], v[190:191]
	v_add_f32_e32 v64, v64, v188
	v_mul_f32_e32 v67, v201, v201
	v_mul_f32_e32 v188, v203, v203
	v_fmac_f32_e32 v67, v200, v200
	v_fmac_f32_e32 v188, v202, v202
	v_add_f32_e32 v67, v67, v188
	v_add_f32_e32 v64, v64, v67
	ds_swizzle_b32 v67, v64 offset:swizzle(SWAP,16)
	v_cvt_pk_bf16_f32 v188, v200, v201
	v_cvt_pk_bf16_f32 v189, v202, v203
	global_store_dwordx4 v[234:235], v[200:203], off offset:528 nt
	global_store_dwordx2 v[192:193], v[188:189], off offset:264
	s_waitcnt lgkmcnt(0)
	v_add_f32_e32 v64, v64, v67
	v_mov_b32_e32 v67, v64
	s_nop 1
	v_permlane32_swap_b32_e32 v64, v67
	s_and_saveexec_b64 s[10:11], s[4:5]
	s_cbranch_execz .LBB0_1096
	v_lshl_add_u64 v[188:189], v[228:229], 2, v[70:71]
	v_add_f32_e32 v64, v64, v67
	global_atomic_add_f32 v[188:189], v64, off offset:512

; __device__ __forceinline__ unsigned cvtpk(float lo, float hi) { f32x2 v = {lo, hi}; bf16x2_t b = __builtin_convertvector(v, bf16x2_t); return __builtin_bit_cast(unsigned, b); }
; #define SWZ_XOR(v, m) __uint_as_float((unsigned)__builtin_amdgcn_ds_swizzle((int)__float_as_uint(v), ((m) << 10) | 0x1f))
; __device__ __forceinline__ float sum32x(float v) { auto rr = __builtin_amdgcn_permlane32_swap(__float_as_uint(v), __float_as_uint(v), false, false); return __uint_as_float(rr[0]) + __uint_as_float(rr[1]); }
;     __device__ __forceinline__ void operator()(const pg8::f32x4 (&acc)[2][2][4][2], const pg8::Unit& u, int wr, int wc, int fr, int fq) const {
;     ...
;                 for (int m = 0; m < 4; ++m) {
;                     const size_t ro = (size_t)(rowb + 128 * ai + 16 * m) * ldc + colb;
;                     float ssr = 0.f;
; #pragma unroll
;                     for (int bj = 0; bj < 2; ++bj)
; #pragma unroll
;                         for (int n = 0; n < 2; ++n) {
;                             const size_t off = ro + 128 * bj + NS * n;
;                             const pg8::f32x4 v = pre[m][bj][n] + acc[ai][bj][m][n] * coef;
;                             *(pg8::f32x4*)(fout + off) = v;
;                             if (flags & 2) { u32x2 w; w.x = cvtpk(v[0], v[1]); w.y = cvtpk(v[2], v[3]); *(u32x2*)(o0 + off) = w; ssr += (v[0] * v[0] + v[1] * v[1]) + (v[2] * v[2] + v[3] * v[3]); }
;                         }
;                     if (flags & 2) { ssr += SWZ_XOR(ssr, 16); ssr = sum32x(ssr); if (fq == 0) atomicAdd((float*)o1 + (rowb + 128 * ai + 16 * m), ssr); }
;                 }
.LBB0_1097:
	s_andn2_b64 vcc, exec, s[10:11]
	s_cbranch_vccnz .LBB0_1099
	v_mov_b32_e32 v67, v66
	v_pk_fma_f32 v[210:211], v[54:55], v[66:67], v[198:199]
	v_pk_fma_f32 v[206:207], v[58:59], v[66:67], v[194:195]
	v_pk_fma_f32 v[202:203], v[50:51], v[66:67], v[190:191]
	global_store_dwordx4 v[234:235], v[208:211], off offset:16 nt
	global_store_dwordx4 v[234:235], v[204:207], off offset:512 nt
	global_store_dwordx4 v[234:235], v[200:203], off offset:528 nt
.LBB0_1099:
	v_lshl_add_u64 v[190:191], v[240:241], 0, v[230:231]
	v_mov_b32_e32 v67, v66
	s_waitcnt vmcnt(11)
	v_pk_fma_f32 v[196:197], v[46:47], v[66:67], v[186:187]
	v_pk_fma_f32 v[194:195], v[44:45], v[232:233], v[184:185]
	v_lshl_add_u64 v[198:199], v[190:191], 2, v[138:139]
	s_mov_b64 s[10:11], -1
	s_and_b64 vcc, exec, s[8:9]
	v_pk_fma_f32 v[192:193], v[36:37], v[232:233], v[180:181]
	s_waitcnt vmcnt(9)
	v_pk_fma_f32 v[188:189], v[40:41], v[232:233], v[176:177]
	v_pk_fma_f32 v[184:185], v[32:33], v[232:233], v[172:173]
	global_store_dwordx4 v[198:199], v[194:197], off nt
	s_cbranch_vccnz .LBB0_1103
	v_cvt_pk_bf16_f32 v172, v194, v195
	v_cvt_pk_bf16_f32 v173, v196, v197
	v_lshl_add_u64 v[176:177], v[190:191], 1, v[68:69]
	global_store_dwordx2 v[176:177], v[172:173], off
	v_mul_f32_e32 v64, v195, v195
	v_mul_f32_e32 v172, v197, v197
	v_fmac_f32_e32 v64, v194, v194
	v_fmac_f32_e32 v172, v196, v196
	v_pk_fma_f32 v[194:195], v[38:39], v[66:67], v[182:183]
	v_add_f32_e32 v64, v64, v172
	v_cvt_pk_bf16_f32 v172, v192, v193
	v_cvt_pk_bf16_f32 v173, v194, v195
	global_store_dwordx4 v[198:199], v[192:195], off offset:16 nt
	global_store_dwordx2 v[176:177], v[172:173], off offset:8
	v_mul_f32_e32 v172, v193, v193
	v_mul_f32_e32 v173, v195, v195
	v_fmac_f32_e32 v172, v192, v192
	v_fmac_f32_e32 v173, v194, v194
	v_add_f32_e32 v172, v172, v173
	v_pk_fma_f32 v[190:191], v[42:43], v[66:67], v[178:179]
	v_add_f32_e32 v64, v64, v172
	v_cvt_pk_bf16_f32 v172, v188, v189
	v_cvt_pk_bf16_f32 v173, v190, v191
	global_store_dwordx4 v[198:199], v[188:191], off offset:512 nt
	global_store_dwordx2 v[176:177], v[172:173], off offset:256
	v_mul_f32_e32 v172, v189, v189
	v_mul_f32_e32 v173, v191, v191
	v_fmac_f32_e32 v172, v188, v188
	v_fmac_f32_e32 v173, v190, v190
	v_add_f32_e32 v172, v172, v173
	v_pk_fma_f32 v[186:187], v[34:35], v[66:67], v[174:175]
	v_add_f32_e32 v64, v64, v172
	v_mul_f32_e32 v67, v185, v185
	v_mul_f32_e32 v172, v187, v187
	v_fmac_f32_e32 v67, v184, v184
	v_fmac_f32_e32 v172, v186, v186
	v_add_f32_e32 v67, v67, v172
	v_add_f32_e32 v64, v64, v67
	ds_swizzle_b32 v67, v64 offset:swizzle(SWAP,16)
	v_cvt_pk_bf16_f32 v172, v184, v185
	v_cvt_pk_bf16_f32 v173, v186, v187
	global_store_dwordx4 v[198:199], v[184:187], off offset:528 nt
	global_store_dwordx2 v[176:177], v[172:173], off offset:264
	s_waitcnt lgkmcnt(0)
	v_add_f32_e32 v64, v64, v67
	v_mov_b32_e32 v67, v64
	s_nop 1
	v_permlane32_swap_b32_e32 v64, v67
	s_and_saveexec_b64 s[10:11], s[4:5]
	s_cbranch_execz .LBB0_1102
	v_lshl_add_u64 v[172:173], v[228:229], 2, v[70:71]
	v_add_f32_e32 v64, v64, v67
	global_atomic_add_f32 v[172:173], v64, off offset:576

; __device__ __forceinline__ unsigned cvtpk(float lo, float hi) { f32x2 v = {lo, hi}; bf16x2_t b = __builtin_convertvector(v, bf16x2_t); return __builtin_bit_cast(unsigned, b); }
; #define SWZ_XOR(v, m) __uint_as_float((unsigned)__builtin_amdgcn_ds_swizzle((int)__float_as_uint(v), ((m) << 10) | 0x1f))
; __device__ __forceinline__ float sum32x(float v) { auto rr = __builtin_amdgcn_permlane32_swap(__float_as_uint(v), __float_as_uint(v), false, false); return __uint_as_float(rr[0]) + __uint_as_float(rr[1]); }
;     __device__ __forceinline__ void operator()(const pg8::f32x4 (&acc)[2][2][4][2], const pg8::Unit& u, int wr, int wc, int fr, int fq) const {
;     ...
;                 for (int m = 0; m < 4; ++m) {
;                     const size_t ro = (size_t)(rowb + 128 * ai + 16 * m) * ldc + colb;
;                     float ssr = 0.f;
; #pragma unroll
;                     for (int bj = 0; bj < 2; ++bj)
; #pragma unroll
;                         for (int n = 0; n < 2; ++n) {
;                             const size_t off = ro + 128 * bj + NS * n;
;                             const pg8::f32x4 v = pre[m][bj][n] + acc[ai][bj][m][n] * coef;
;                             *(pg8::f32x4*)(fout + off) = v;
;                             if (flags & 2) { u32x2 w; w.x = cvtpk(v[0], v[1]); w.y = cvtpk(v[2], v[3]); *(u32x2*)(o0 + off) = w; ssr += (v[0] * v[0] + v[1] * v[1]) + (v[2] * v[2] + v[3] * v[3]); }
;                         }
;                     if (flags & 2) { ssr += SWZ_XOR(ssr, 16); ssr = sum32x(ssr); if (fq == 0) atomicAdd((float*)o1 + (rowb + 128 * ai + 16 * m), ssr); }
;                 }
.LBB0_1103:
	s_andn2_b64 vcc, exec, s[10:11]
	s_cbranch_vccnz .LBB0_1105
	v_mov_b32_e32 v67, v66
	v_pk_fma_f32 v[194:195], v[38:39], v[66:67], v[182:183]
	v_pk_fma_f32 v[190:191], v[42:43], v[66:67], v[178:179]
	v_pk_fma_f32 v[186:187], v[34:35], v[66:67], v[174:175]
	global_store_dwordx4 v[198:199], v[192:195], off offset:16 nt
	global_store_dwordx4 v[198:199], v[188:191], off offset:512 nt
	global_store_dwordx4 v[198:199], v[184:187], off offset:528 nt
.LBB0_1105:
	v_lshl_add_u64 v[174:175], v[238:239], 0, v[230:231]
	v_mov_b32_e32 v67, v66
	s_waitcnt vmcnt(8)
	v_pk_fma_f32 v[180:181], v[30:31], v[66:67], v[170:171]
	v_pk_fma_f32 v[178:179], v[28:29], v[232:233], v[168:169]
	v_lshl_add_u64 v[182:183], v[174:175], 2, v[138:139]
	s_mov_b64 s[10:11], -1
	s_and_b64 vcc, exec, s[8:9]
	v_pk_fma_f32 v[176:177], v[20:21], v[232:233], v[164:165]
	s_waitcnt vmcnt(6)
	v_pk_fma_f32 v[172:173], v[24:25], v[232:233], v[160:161]
	v_pk_fma_f32 v[168:169], v[16:17], v[232:233], v[156:157]
	global_store_dwordx4 v[182:183], v[178:181], off nt
	s_cbranch_vccnz .LBB0_1109
	v_cvt_pk_bf16_f32 v156, v178, v179
	v_cvt_pk_bf16_f32 v157, v180, v181
	v_lshl_add_u64 v[160:161], v[174:175], 1, v[68:69]
	global_store_dwordx2 v[160:161], v[156:157], off
	v_mul_f32_e32 v64, v179, v179
	v_mul_f32_e32 v156, v181, v181
	v_fmac_f32_e32 v64, v178, v178
	v_fmac_f32_e32 v156, v180, v180
	v_pk_fma_f32 v[178:179], v[22:23], v[66:67], v[166:167]
	v_add_f32_e32 v64, v64, v156
	v_cvt_pk_bf16_f32 v156, v176, v177
	v_cvt_pk_bf16_f32 v157, v178, v179
	global_store_dwordx4 v[182:183], v[176:179], off offset:16 nt
	global_store_dwordx2 v[160:161], v[156:157], off offset:8
	v_mul_f32_e32 v156, v177, v177
	v_mul_f32_e32 v157, v179, v179
	v_fmac_f32_e32 v156, v176, v176
	v_fmac_f32_e32 v157, v178, v178
	v_add_f32_e32 v156, v156, v157
	v_pk_fma_f32 v[174:175], v[26:27], v[66:67], v[162:163]
	v_add_f32_e32 v64, v64, v156
	v_cvt_pk_bf16_f32 v156, v172, v173
	v_cvt_pk_bf16_f32 v157, v174, v175
	global_store_dwordx4 v[182:183], v[172:175], off offset:512 nt
	global_store_dwordx2 v[160:161], v[156:157], off offset:256
	v_mul_f32_e32 v156, v173, v173
	v_mul_f32_e32 v157, v175, v175
	v_fmac_f32_e32 v156, v172, v172
	v_fmac_f32_e32 v157, v174, v174
	v_add_f32_e32 v156, v156, v157
	v_pk_fma_f32 v[170:171], v[18:19], v[66:67], v[158:159]
	v_add_f32_e32 v64, v64, v156
	v_mul_f32_e32 v67, v169, v169
	v_mul_f32_e32 v156, v171, v171
	v_fmac_f32_e32 v67, v168, v168
	v_fmac_f32_e32 v156, v170, v170
	v_add_f32_e32 v67, v67, v156
	v_add_f32_e32 v64, v64, v67
	ds_swizzle_b32 v67, v64 offset:swizzle(SWAP,16)
	v_cvt_pk_bf16_f32 v156, v168, v169
	v_cvt_pk_bf16_f32 v157, v170, v171
	global_store_dwordx4 v[182:183], v[168:171], off offset:528 nt
	global_store_dwordx2 v[160:161], v[156:157], off offset:264
	s_waitcnt lgkmcnt(0)
	v_add_f32_e32 v64, v64, v67
	v_mov_b32_e32 v67, v64
	s_nop 1
	v_permlane32_swap_b32_e32 v64, v67
	s_and_saveexec_b64 s[10:11], s[4:5]
	s_cbranch_execz .LBB0_1108
	v_lshl_add_u64 v[156:157], v[228:229], 2, v[70:71]
	v_add_f32_e32 v64, v64, v67
	global_atomic_add_f32 v[156:157], v64, off offset:640

; __device__ __forceinline__ unsigned cvtpk(float lo, float hi) { f32x2 v = {lo, hi}; bf16x2_t b = __builtin_convertvector(v, bf16x2_t); return __builtin_bit_cast(unsigned, b); }
; #define SWZ_XOR(v, m) __uint_as_float((unsigned)__builtin_amdgcn_ds_swizzle((int)__float_as_uint(v), ((m) << 10) | 0x1f))
; __device__ __forceinline__ float sum32x(float v) { auto rr = __builtin_amdgcn_permlane32_swap(__float_as_uint(v), __float_as_uint(v), false, false); return __uint_as_float(rr[0]) + __uint_as_float(rr[1]); }
;     __device__ __forceinline__ void operator()(const pg8::f32x4 (&acc)[2][2][4][2], const pg8::Unit& u, int wr, int wc, int fr, int fq) const {
;     ...
;                 for (int m = 0; m < 4; ++m) {
;                     const size_t ro = (size_t)(rowb + 128 * ai + 16 * m) * ldc + colb;
;                     float ssr = 0.f;
; #pragma unroll
;                     for (int bj = 0; bj < 2; ++bj)
; #pragma unroll
;                         for (int n = 0; n < 2; ++n) {
;                             const size_t off = ro + 128 * bj + NS * n;
;                             const pg8::f32x4 v = pre[m][bj][n] + acc[ai][bj][m][n] * coef;
;                             *(pg8::f32x4*)(fout + off) = v;
;                             if (flags & 2) { u32x2 w; w.x = cvtpk(v[0], v[1]); w.y = cvtpk(v[2], v[3]); *(u32x2*)(o0 + off) = w; ssr += (v[0] * v[0] + v[1] * v[1]) + (v[2] * v[2] + v[3] * v[3]); }
;                         }
;                     if (flags & 2) { ssr += SWZ_XOR(ssr, 16); ssr = sum32x(ssr); if (fq == 0) atomicAdd((float*)o1 + (rowb + 128 * ai + 16 * m), ssr); }
;                 }
.LBB0_1109:
	s_andn2_b64 vcc, exec, s[10:11]
	s_cbranch_vccnz .LBB0_1111
	v_mov_b32_e32 v67, v66
	v_pk_fma_f32 v[178:179], v[22:23], v[66:67], v[166:167]
	v_pk_fma_f32 v[174:175], v[26:27], v[66:67], v[162:163]
	v_pk_fma_f32 v[170:171], v[18:19], v[66:67], v[158:159]
	global_store_dwordx4 v[182:183], v[176:179], off offset:16 nt
	global_store_dwordx4 v[182:183], v[172:175], off offset:512 nt
	global_store_dwordx4 v[182:183], v[168:171], off offset:528 nt
.LBB0_1111:
	v_lshl_add_u64 v[164:165], v[236:237], 0, v[230:231]
	v_mov_b32_e32 v67, v66
	s_waitcnt vmcnt(5)
	v_pk_fma_f32 v[160:161], v[14:15], v[66:67], v[154:155]
	v_pk_fma_f32 v[158:159], v[12:13], v[232:233], v[152:153]
	v_lshl_add_u64 v[162:163], v[164:165], 2, v[138:139]
	s_mov_b64 s[10:11], -1
	s_and_b64 vcc, exec, s[8:9]
	v_pk_fma_f32 v[156:157], v[4:5], v[232:233], v[148:149]
	s_waitcnt vmcnt(3)
	v_pk_fma_f32 v[152:153], v[8:9], v[232:233], v[144:145]
	v_pk_fma_f32 v[138:139], v[0:1], v[232:233], v[140:141]
	global_store_dwordx4 v[162:163], v[158:161], off nt
	s_cbranch_vccnz .LBB0_1115
	v_cvt_pk_bf16_f32 v140, v158, v159
	v_cvt_pk_bf16_f32 v141, v160, v161
	v_lshl_add_u64 v[144:145], v[164:165], 1, v[68:69]
	global_store_dwordx2 v[144:145], v[140:141], off
	v_mul_f32_e32 v64, v159, v159
	v_mul_f32_e32 v140, v161, v161
	v_fmac_f32_e32 v64, v158, v158
	v_fmac_f32_e32 v140, v160, v160
	v_pk_fma_f32 v[158:159], v[6:7], v[66:67], v[150:151]
	v_add_f32_e32 v64, v64, v140
	v_cvt_pk_bf16_f32 v140, v156, v157
	v_cvt_pk_bf16_f32 v141, v158, v159
	global_store_dwordx4 v[162:163], v[156:159], off offset:16 nt
	global_store_dwordx2 v[144:145], v[140:141], off offset:8
	v_mul_f32_e32 v140, v157, v157
	v_mul_f32_e32 v141, v159, v159
	v_fmac_f32_e32 v140, v156, v156
	v_fmac_f32_e32 v141, v158, v158
	v_add_f32_e32 v140, v140, v141
	v_pk_fma_f32 v[154:155], v[10:11], v[66:67], v[146:147]
	v_add_f32_e32 v64, v64, v140
	v_cvt_pk_bf16_f32 v140, v152, v153
	v_cvt_pk_bf16_f32 v141, v154, v155
	global_store_dwordx4 v[162:163], v[152:155], off offset:512 nt
	global_store_dwordx2 v[144:145], v[140:141], off offset:256
	v_mul_f32_e32 v140, v153, v153
	v_mul_f32_e32 v141, v155, v155
	v_fmac_f32_e32 v140, v152, v152
	v_fmac_f32_e32 v141, v154, v154
	v_add_f32_e32 v140, v140, v141
	v_add_f32_e32 v64, v64, v140
	v_pk_fma_f32 v[140:141], v[2:3], v[66:67], v[142:143]
	v_mul_f32_e32 v67, v139, v139
	v_mul_f32_e32 v148, v141, v141
	v_fmac_f32_e32 v67, v138, v138
	v_fmac_f32_e32 v148, v140, v140
	v_add_f32_e32 v67, v67, v148
	v_add_f32_e32 v64, v64, v67
	ds_swizzle_b32 v67, v64 offset:swizzle(SWAP,16)
	v_cvt_pk_bf16_f32 v148, v138, v139
	v_cvt_pk_bf16_f32 v149, v140, v141
	global_store_dwordx4 v[162:163], v[138:141], off offset:528 nt
	global_store_dwordx2 v[144:145], v[148:149], off offset:264
	s_waitcnt lgkmcnt(0)
	v_add_f32_e32 v64, v64, v67
	v_mov_b32_e32 v67, v64
	s_nop 1
	v_permlane32_swap_b32_e32 v64, v67
	s_and_saveexec_b64 s[8:9], s[4:5]
	s_cbranch_execz .LBB0_1114
	v_lshl_add_u64 v[70:71], v[228:229], 2, v[70:71]
	v_add_f32_e32 v64, v64, v67
	global_atomic_add_f32 v[70:71], v64, off offset:704

;     __device__ __forceinline__ void operator()(const pg8::f32x4 (&acc)[2][2][4][2], const pg8::Unit& u, int wr, int wc, int fr, int fq) const {
;     ...
;                             const size_t off = ro + 128 * bj + NS * n;
;                             const pg8::f32x4 v = pre[m][bj][n] + acc[ai][bj][m][n] * coef;
;                             *(pg8::f32x4*)(fout + off) = v;
.LBB0_1115:
	s_andn2_b64 vcc, exec, s[10:11]
	s_cbranch_vccnz .LBB0_1117
	v_mov_b32_e32 v67, v66
	v_pk_fma_f32 v[158:159], v[6:7], v[66:67], v[150:151]
	v_pk_fma_f32 v[154:155], v[10:11], v[66:67], v[146:147]
	v_pk_fma_f32 v[140:141], v[2:3], v[66:67], v[142:143]
	global_store_dwordx4 v[162:163], v[156:159], off offset:16 nt
	global_store_dwordx4 v[162:163], v[152:155], off offset:512 nt
	global_store_dwordx4 v[162:163], v[138:141], off offset:528 nt

; __device__ __forceinline__ unsigned cvtpk(float lo, float hi) { f32x2 v = {lo, hi}; bf16x2_t b = __builtin_convertvector(v, bf16x2_t); return __builtin_bit_cast(unsigned, b); }
; #define SWZ_XOR(v, m) __uint_as_float((unsigned)__builtin_amdgcn_ds_swizzle((int)__float_as_uint(v), ((m) << 10) | 0x1f))
; __device__ __forceinline__ float sum32x(float v) { auto rr = __builtin_amdgcn_permlane32_swap(__float_as_uint(v), __float_as_uint(v), false, false); return __uint_as_float(rr[0]) + __uint_as_float(rr[1]); }
;     __device__ __forceinline__ void operator()(const pg8::f32x4 (&acc)[2][2][4][2], const pg8::Unit& u, int wr, int wc, int fr, int fq) const {
;     ...
;                 for (int m = 0; m < 4; ++m) {
;                     const size_t ro = (size_t)(rowb + 128 * ai + 16 * m) * ldc + colb;
;                     float ssr = 0.f;
; #pragma unroll
;                     for (int bj = 0; bj < 2; ++bj)
; #pragma unroll
;                         for (int n = 0; n < 2; ++n) {
;                             const size_t off = ro + 128 * bj + NS * n;
;                             const pg8::f32x4 v = pre[m][bj][n] + acc[ai][bj][m][n] * coef;
;                             *(pg8::f32x4*)(fout + off) = v;
;                             if (flags & 2) { u32x2 w; w.x = cvtpk(v[0], v[1]); w.y = cvtpk(v[2], v[3]); *(u32x2*)(o0 + off) = w; ssr += (v[0] * v[0] + v[1] * v[1]) + (v[2] * v[2] + v[3] * v[3]); }
;                         }
;                     if (flags & 2) { ssr += SWZ_XOR(ssr, 16); ssr = sum32x(ssr); if (fq == 0) atomicAdd((float*)o1 + (rowb + 128 * ai + 16 * m), ssr); }
;                 }
.LBB0_1191:
	v_lshl_add_u64 v[190:191], v[240:241], 0, v[230:231]
	v_mov_b32_e32 v67, v66
	v_cndmask_b32_e64 v64, 0, 1, s[10:11]
	s_waitcnt vmcnt(11)
	v_pk_fma_f32 v[196:197], v[118:119], v[66:67], v[186:187]
	v_pk_fma_f32 v[194:195], v[116:117], v[232:233], v[184:185]
	v_lshl_add_u64 v[198:199], v[190:191], 2, v[138:139]
	s_mov_b64 s[56:57], -1
	v_cmp_ne_u32_e64 s[8:9], 1, v64
	s_andn2_b64 vcc, exec, s[10:11]
	v_pk_fma_f32 v[192:193], v[108:109], v[232:233], v[180:181]
	s_waitcnt vmcnt(9)
	v_pk_fma_f32 v[188:189], v[112:113], v[232:233], v[176:177]
	v_pk_fma_f32 v[184:185], v[104:105], v[232:233], v[172:173]
	global_store_dwordx4 v[198:199], v[194:197], off nt
	s_cbranch_vccnz .LBB0_1195
	v_cvt_pk_bf16_f32 v172, v194, v195
	v_cvt_pk_bf16_f32 v173, v196, v197
	v_lshl_add_u64 v[176:177], v[190:191], 1, v[68:69]
	global_store_dwordx2 v[176:177], v[172:173], off
	v_mul_f32_e32 v64, v195, v195
	v_mul_f32_e32 v172, v197, v197
	v_fmac_f32_e32 v64, v194, v194
	v_fmac_f32_e32 v172, v196, v196
	v_pk_fma_f32 v[194:195], v[110:111], v[66:67], v[182:183]
	v_add_f32_e32 v64, v64, v172
	v_cvt_pk_bf16_f32 v172, v192, v193
	v_cvt_pk_bf16_f32 v173, v194, v195
	global_store_dwordx4 v[198:199], v[192:195], off offset:16 nt
	global_store_dwordx2 v[176:177], v[172:173], off offset:8
	v_mul_f32_e32 v172, v193, v193
	v_mul_f32_e32 v173, v195, v195
	v_fmac_f32_e32 v172, v192, v192
	v_fmac_f32_e32 v173, v194, v194
	v_add_f32_e32 v172, v172, v173
	v_pk_fma_f32 v[190:191], v[114:115], v[66:67], v[178:179]
	v_add_f32_e32 v64, v64, v172
	v_cvt_pk_bf16_f32 v172, v188, v189
	v_cvt_pk_bf16_f32 v173, v190, v191
	global_store_dwordx4 v[198:199], v[188:191], off offset:512 nt
	global_store_dwordx2 v[176:177], v[172:173], off offset:256
	v_mul_f32_e32 v172, v189, v189
	v_mul_f32_e32 v173, v191, v191
	v_fmac_f32_e32 v172, v188, v188
	v_fmac_f32_e32 v173, v190, v190
	v_add_f32_e32 v172, v172, v173
	v_pk_fma_f32 v[186:187], v[106:107], v[66:67], v[174:175]
	v_add_f32_e32 v64, v64, v172
	v_mul_f32_e32 v67, v185, v185
	v_mul_f32_e32 v172, v187, v187
	v_fmac_f32_e32 v67, v184, v184
	v_fmac_f32_e32 v172, v186, v186
	v_add_f32_e32 v67, v67, v172
	v_add_f32_e32 v64, v64, v67
	ds_swizzle_b32 v67, v64 offset:swizzle(SWAP,16)
	v_cvt_pk_bf16_f32 v172, v184, v185
	v_cvt_pk_bf16_f32 v173, v186, v187
	global_store_dwordx4 v[198:199], v[184:187], off offset:528 nt
	global_store_dwordx2 v[176:177], v[172:173], off offset:264
	s_waitcnt lgkmcnt(0)
	v_add_f32_e32 v64, v64, v67
	v_mov_b32_e32 v67, v64
	s_nop 1
	v_permlane32_swap_b32_e32 v64, v67
	s_and_saveexec_b64 s[10:11], s[4:5]
	s_cbranch_execz .LBB0_1194
	v_lshl_add_u64 v[172:173], v[228:229], 2, v[70:71]
	v_add_f32_e32 v64, v64, v67
	global_atomic_add_f32 v[172:173], v64, off offset:64

;     __device__ __forceinline__ void operator()(const pg8::f32x4 (&acc)[2][2][4][2], const pg8::Unit& u, int wr, int wc, int fr, int fq) const {
;     ...
;                             const size_t off = ro + 128 * bj + NS * n;
;                             const pg8::f32x4 v = pre[m][bj][n] + acc[ai][bj][m][n] * coef;
;                             *(pg8::f32x4*)(fout + off) = v;
.LBB0_1195:
	s_andn2_b64 vcc, exec, s[56:57]
	s_cbranch_vccnz .LBB0_1197
	v_mov_b32_e32 v67, v66
	v_pk_fma_f32 v[194:195], v[110:111], v[66:67], v[182:183]
	v_pk_fma_f32 v[190:191], v[114:115], v[66:67], v[178:179]
	v_pk_fma_f32 v[186:187], v[106:107], v[66:67], v[174:175]
	global_store_dwordx4 v[198:199], v[192:195], off offset:16 nt
	global_store_dwordx4 v[198:199], v[188:191], off offset:512 nt
	global_store_dwordx4 v[198:199], v[184:187], off offset:528 nt
